# SS_TAIL 530->742: seven state items per idle workgroup in P12's tail, P11 keeps 282 items
# baseline (speedup 1.0000x reference)
; __device__ __forceinline__ float* karg_out() { return *(volatile KAS fptr_t*)((const KAS char*)__builtin_amdgcn_kernarg_segment_ptr() + 256); }
; #define INP(k) karg_in(k)
; #define lane opq(lane_now())
; #define tid opq((wave << 6) | lane_now())
; __global__ void __launch_bounds__(NTHR, 2) fwd_megakernel(Params P) {
;     ...
;     if constexpr ((PHM >> 11) & 1) {
;     sample_norm_rows<0>(INP(28), 6, gw, lane);
;     {
;         for (int item = (G == 256 ? SS_TAIL : 0) + wg; item < NS * NH; item += G) delta_sample_item<1>(P, lds, item, tid);
;         const int gt = wg * NTHR + tid, NGT = G * NTHR;
;         for (int i = gt; i < NS * 3 * 3072; i += NGT) { const int bs = i / 9216, j = (i / 3072) % 3, c3 = i % 3072;
;             karg_out()[O_CQS + i] = j < 2 ? INP(7)[(size_t)bs * 9216 + (j + 1) * 3072 + c3] : bf2f(Z[(size_t)(2 + (c3 >> 10)) * (ZB / 2) + ((size_t)MPR + bs) * D + (c3 & 1023)]); }
.LBB0_2103:
	v_readlane_b32 s4, v238, 18
	v_readlane_b32 s5, v238, 19
	s_and_b64 s[4:5], exec, s[4:5]
	s_cselect_b32 s4, 0x2e6, 0
	s_mov_b32 s3, s2
	s_cmpk_lg_u32 s78, 0x100
	s_cbranch_scc1 .Lp11_norot
	s_add_i32 s3, s2, 0xf0
	s_and_b32 s3, s3, 0xff

; __device__ __forceinline__ unsigned f2bf(float f) { return pk2(f, f) & 0xffffu; }
; __device__ __forceinline__ float rsq_f(float x) { return __builtin_amdgcn_rsqf(x); }
; __device__ __forceinline__ float sigmoid_f(float x) { return rcp_f(1.f + __expf(-x)); }
; __device__ __forceinline__ float softplus_f(float x) { return x > 20.f ? x : log1pf(__expf(x)); }
; __device__ __forceinline__ float* karg_out() { return *(volatile KAS fptr_t*)((const KAS char*)__builtin_amdgcn_kernarg_segment_ptr() + 256); }
; __device__ __forceinline__ unsigned char* karg_ws() { return *(volatile KAS ucptr_t*)((const KAS char*)__builtin_amdgcn_kernarg_segment_ptr() + 264); }
; #define INP(k) karg_in(k)
; #define lane opq(lane_now())
; #define tid opq((wave << 6) | lane_now())
; template <int MODE>
; __device__ __forceinline__ void delta_sample_item(const Params& P, LAS unsigned char* lds, int item, int tid) {
;     ...
;     pk = (rpk[v] + rpk[128 + v]) + (rpk[256 + v] + rpk[384 + v]); pq = (rpq[v] + rpq[128 + v]) + (rpq[256 + v] + rpq[384 + v]);
;     const float* ABL = (const float*)(karg_ws() + WS_ABL);
;     const float al = ABL[row * 16 + h], bl = ABL[row * 16 + 8 + h];
;     const float dc = __expf(-__expf(INP(23)[h]) * softplus_f(al + INP(24)[h])), be = sigmoid_f(bl);
;     const float delta = be * (tmp[256 + v] - dc * pk);
;     if (MODE == 0) {
;         const float o = dc * pq + kq * delta; const float so = wave_sum(o * o);
;         if (lane == 0 && wave < 2) scl[4 + wave] = so;
;         __syncthreads();
;         if (kg == 0) { bf16* zp = (bf16*)(karg_ws() + WS_Z + 5 * ZB) + row * D + h * 128 + v;
;             *zp = (bf16)f2bf(o * rsq_f((scl[4] + scl[5]) * (1.f / 128.f) + EPS) * INP(25)[v] * bf2f(*zp)); } }
;     else { float* So = karg_out() + O_SS + ((size_t)(bs * NH + h) * 128 + kg * 32) * 128 + v;
; #pragma unroll
;         for (int j = 0; j < 32; ++j) __builtin_nontemporal_store(dc * S[j] + (tmp[128 + kg * 32 + j] * sk) * delta, So + (size_t)j * 128); }
; __global__ void __launch_bounds__(NTHR, 2) fwd_megakernel(Params P) {
;     ...
;       if (G == 256 && wg >= 150) for (int item = wg - 150; item < SS_TAIL; item += 106) delta_sample_item<1>(P, lds, item, tid); }
.LBB0_2226:
	s_cmpk_gt_i32 s2, 0x95
	v_readlane_b32 s6, v238, 18
	s_cselect_b64 s[4:5], -1, 0
	v_readlane_b32 s7, v238, 19
	s_and_b64 s[4:5], s[4:5], s[6:7]
	s_cmpk_lt_u32 s2, 0x37c
	s_cselect_b64 s[6:7], -1, 0
	s_and_b64 s[4:5], s[4:5], s[6:7]
	s_andn2_b64 vcc, exec, s[4:5]
	s_cbranch_vccnz .LBB0_2248
	s_ashr_i32 s3, s2, 31
	s_add_i32 s18, s2, 0xffffff00
	s_lshl_b64 s[4:5], s[2:3], 16
	s_add_u32 s10, s4, 0x3d8be00
	s_addc_u32 s11, s5, 0
	s_movk_i32 s3, 0x180
	s_mov_b32 s19, 0x2040000
	s_mov_b32 s13, 0
	v_mov_b32_e32 v1, 0
	s_mov_b32 s20, 0x90c0000
	s_mov_b32 s21, 0x9000
	s_movk_i32 s22, 0x3000
	s_movk_i32 s23, 0x6000
	s_mov_b32 s24, 0xfb915000
	s_mov_b32 s25, 0xfb916000
	s_mov_b32 s26, 0xfb917000
	s_mov_b32 s27, 0xfb918000
	v_mov_b32_e32 v12, 0x2e00000
	s_mov_b32 s28, 0x41a00000
	s_mov_b32 s29, 0x3f2aaaab
	v_mov_b32_e32 v13, 0x3ecc95a3
	s_mov_b32 s30, 0x3f317218
	s_mov_b32 s31, 0x7f800000
	s_mov_b32 s34, 0x33800000
	s_movk_i32 s35, 0xd000
	s_movk_i32 s36, 0xe000
	s_movk_i32 s37, 0xf000
	v_mov_b32_e32 v14, 0x300
	v_mov_b32_e32 v2, 0x3f317218
	v_mov_b32_e32 v15, 0x7f800000
	v_mov_b32_e32 v16, 0x7fc00000
	v_mov_b32_e32 v17, 0xff800000
	s_branch .LBB0_2229
.LBB0_2228:
	v_mul_f32_e32 v51, 0x3fb8aa3b, v51
	v_exp_f32_e32 v51, v51
	v_add_f32_e32 v8, v8, v9
	v_add_f32_e32 v9, v10, v11
	v_mul_f32_e32 v10, 0xbfb8aa3b, v50
	v_exp_f32_e32 v10, v10
	v_mul_f32_e32 v3, v3, v51
	v_mul_f32_e32 v3, 0xbfb8aa3b, v3
	ds_read_b32 v4, v4 offset:1024
	v_exp_f32_e32 v3, v3
	v_add_f32_e32 v10, 1.0, v10
	v_rcp_f32_e32 v10, v10
	v_add_f32_e32 v8, v8, v9
	s_load_dwordx2 s[4:5], s[0:1], 0x100
	s_waitcnt lgkmcnt(0)
	v_fma_f32 v4, -v8, v3, v4
	v_mul_f32_e32 v4, v10, v4
	ds_read_b128 v[8:11], v25 offset:512
	ds_read_b128 v[50:53], v25 offset:528
	ds_read_b128 v[54:57], v25 offset:544
	v_lshl_add_u64 v[6:7], s[4:5], 0, v[6:7]
	v_lshl_add_u64 v[58:59], v[6:7], 0, s[10:11]
	s_add_u32 s10, s10, 0x6a0000
	s_waitcnt lgkmcnt(2)
	v_mul_f32_e32 v6, v5, v8
	v_mul_f32_e32 v8, v6, v4
	v_add_co_u32_e32 v6, vcc, s35, v58
	v_fmac_f32_e32 v8, v49, v3
	s_nop 0
	v_addc_co_u32_e32 v7, vcc, -1, v59, vcc
	global_store_dword v[6:7], v8, off offset:-3584 nt
	v_mul_f32_e32 v8, v5, v9
	v_mul_f32_e32 v8, v4, v8
	v_fmac_f32_e32 v8, v48, v3
	global_store_dword v[6:7], v8, off offset:-3072 nt
	v_mul_f32_e32 v8, v5, v10
	v_mul_f32_e32 v8, v4, v8
	v_fmac_f32_e32 v8, v47, v3
	global_store_dword v[6:7], v8, off offset:-2560 nt
	v_mul_f32_e32 v8, v5, v11
	v_mul_f32_e32 v8, v4, v8
	v_fmac_f32_e32 v8, v46, v3
	global_store_dword v[6:7], v8, off offset:-2048 nt
	s_waitcnt lgkmcnt(1)
	v_mul_f32_e32 v8, v5, v50
	v_mul_f32_e32 v8, v4, v8
	v_fmac_f32_e32 v8, v45, v3
	global_store_dword v[6:7], v8, off offset:-1536 nt
	v_mul_f32_e32 v8, v5, v51
	v_mul_f32_e32 v8, v4, v8
	v_fmac_f32_e32 v8, v44, v3
	global_store_dword v[6:7], v8, off offset:-1024 nt
	v_mul_f32_e32 v8, v5, v52
	v_mul_f32_e32 v8, v4, v8
	v_fmac_f32_e32 v8, v42, v3
	global_store_dword v[6:7], v8, off offset:-512 nt
	v_mul_f32_e32 v6, v5, v53
	v_mul_f32_e32 v6, v4, v6
	v_add_co_u32_e32 v10, vcc, s36, v58
	s_waitcnt lgkmcnt(0)
	v_mul_f32_e32 v42, v5, v54
	v_fmac_f32_e32 v6, v43, v3
	v_addc_co_u32_e32 v11, vcc, -1, v59, vcc
	v_mul_f32_e32 v42, v4, v42
	global_store_dword v[10:11], v6, off offset:-4096 nt
	ds_read_b128 v[6:9], v25 offset:560
	v_fmac_f32_e32 v42, v41, v3
	v_mul_f32_e32 v41, v5, v55
	v_mul_f32_e32 v41, v4, v41
	v_fmac_f32_e32 v41, v40, v3
	v_mul_f32_e32 v40, v5, v56
	v_mul_f32_e32 v40, v4, v40
	v_fmac_f32_e32 v40, v39, v3
	v_mul_f32_e32 v39, v5, v57
	v_mul_f32_e32 v39, v4, v39
	s_waitcnt lgkmcnt(0)
	v_mul_f32_e32 v6, v5, v6
	v_fmac_f32_e32 v39, v38, v3
	v_mul_f32_e32 v6, v4, v6
	global_store_dword v[10:11], v42, off offset:-3584 nt
	global_store_dword v[10:11], v41, off offset:-3072 nt
	global_store_dword v[10:11], v40, off offset:-2560 nt
	global_store_dword v[10:11], v39, off offset:-2048 nt
	v_fmac_f32_e32 v6, v37, v3
	ds_read_b128 v[38:41], v25 offset:576
	ds_read_b128 v[42:45], v25 offset:592
	ds_read_b128 v[46:49], v25 offset:608
	global_store_dword v[10:11], v6, off offset:-1536 nt
	v_mul_f32_e32 v6, v5, v7
	v_mul_f32_e32 v6, v4, v6
	v_fmac_f32_e32 v6, v36, v3
	global_store_dword v[10:11], v6, off offset:-1024 nt
	v_mul_f32_e32 v6, v5, v8
	v_mul_f32_e32 v6, v4, v6
	v_fmac_f32_e32 v6, v35, v3
	global_store_dword v[10:11], v6, off offset:-512 nt
	v_mul_f32_e32 v6, v5, v9
	v_mul_f32_e32 v6, v4, v6
	v_fmac_f32_e32 v6, v33, v3
	global_store_dword v[10:11], v6, off nt
	s_waitcnt lgkmcnt(2)
	v_mul_f32_e32 v6, v5, v38
	v_mul_f32_e32 v8, v4, v6
	v_add_co_u32_e32 v6, vcc, s37, v58
	v_fmac_f32_e32 v8, v34, v3
	s_nop 0
	v_addc_co_u32_e32 v7, vcc, -1, v59, vcc
	global_store_dword v[6:7], v8, off offset:-3584 nt
	v_mul_f32_e32 v8, v5, v39
	v_mul_f32_e32 v8, v4, v8
	v_fmac_f32_e32 v8, v32, v3
	global_store_dword v[6:7], v8, off offset:-3072 nt
	v_mul_f32_e32 v8, v5, v40
	v_mul_f32_e32 v8, v4, v8
	v_fmac_f32_e32 v8, v31, v3
	global_store_dword v[6:7], v8, off offset:-2560 nt
	v_mul_f32_e32 v8, v5, v41
	v_mul_f32_e32 v8, v4, v8
	v_fmac_f32_e32 v8, v30, v3
	global_store_dword v[6:7], v8, off offset:-2048 nt
	s_waitcnt lgkmcnt(1)
	v_mul_f32_e32 v8, v5, v42
	v_mul_f32_e32 v8, v4, v8
	v_fmac_f32_e32 v8, v29, v3
	global_store_dword v[6:7], v8, off offset:-1536 nt
	v_mul_f32_e32 v8, v5, v43
	v_mul_f32_e32 v8, v4, v8
	v_fmac_f32_e32 v8, v28, v3
	global_store_dword v[6:7], v8, off offset:-1024 nt
	v_mul_f32_e32 v8, v5, v44
	v_mul_f32_e32 v8, v4, v8
	v_fmac_f32_e32 v8, v26, v3
	global_store_dword v[6:7], v8, off offset:-512 nt
	v_mul_f32_e32 v6, v5, v45
	v_mul_f32_e32 v6, v4, v6
	v_fmac_f32_e32 v6, v27, v3
	global_store_dword v[58:59], v6, off offset:-4096 nt
	ds_read_b128 v[6:9], v25 offset:624
	s_waitcnt lgkmcnt(1)
	v_mul_f32_e32 v10, v5, v46
	v_mul_f32_e32 v10, v4, v10
	v_fmac_f32_e32 v10, v24, v3
	global_store_dword v[58:59], v10, off offset:-3584 nt
	v_mul_f32_e32 v10, v5, v47
	s_waitcnt lgkmcnt(0)
	v_mul_f32_e32 v6, v5, v6
	v_mul_f32_e32 v10, v4, v10
	v_mul_f32_e32 v6, v4, v6
	v_fmac_f32_e32 v10, v23, v3
	v_fmac_f32_e32 v6, v20, v3
	global_store_dword v[58:59], v10, off offset:-3072 nt
	v_mul_f32_e32 v10, v5, v48
	global_store_dword v[58:59], v6, off offset:-1536 nt
	v_mul_f32_e32 v6, v5, v7
	v_mul_f32_e32 v10, v4, v10
	v_mul_f32_e32 v6, v4, v6
	v_fmac_f32_e32 v10, v22, v3
	v_fmac_f32_e32 v6, v19, v3
	global_store_dword v[58:59], v10, off offset:-2560 nt
	v_mul_f32_e32 v10, v5, v49
	global_store_dword v[58:59], v6, off offset:-1024 nt
	v_mul_f32_e32 v6, v5, v8
	v_mul_f32_e32 v5, v5, v9
	v_mul_f32_e32 v10, v4, v10
	v_mul_f32_e32 v6, v4, v6
	v_mul_f32_e32 v4, v4, v5
	s_addc_u32 s11, s11, 0
	v_fmac_f32_e32 v10, v21, v3
	v_fmac_f32_e32 v6, v18, v3
	v_fmac_f32_e32 v4, v0, v3
	s_cmpk_lt_i32 s18, 0x27c
	global_store_dword v[58:59], v10, off offset:-2048 nt
	global_store_dword v[58:59], v6, off offset:-512 nt
	global_store_dword v[58:59], v4, off nt
	s_barrier
	s_cbranch_scc0 .LBB0_2248
